# per-half grid barrier: waiting workgroups poll the top-level generation word directly (one release hop fewer)
# baseline (speedup 1.0000x reference)
.LBB0_951:
	s_or_b64 exec, exec, s[10:11]
	v_cvt_f32_u32_e32 v4, v2
	s_waitcnt vmcnt(0)
	v_readfirstlane_b32 s8, v3
	v_sub_u32_e32 v3, 0, v2
	v_rcp_iflag_f32_e32 v4, v4
	v_add_u32_e32 v5, s8, v1
	v_mul_f32_e32 v4, 0x4f7ffffe, v4
	v_cvt_u32_f32_e32 v4, v4
	v_mul_lo_u32 v1, v3, v4
	v_mul_hi_u32 v1, v4, v1
	v_add_u32_e32 v1, v4, v1
	v_mul_hi_u32 v1, v5, v1
	v_mul_lo_u32 v3, v1, v2
	v_sub_u32_e32 v3, v5, v3
	v_add_u32_e32 v4, 1, v1
	v_cmp_ge_u32_e32 vcc, v3, v2
	s_nop 1
	v_cndmask_b32_e32 v1, v1, v4, vcc
	v_sub_u32_e32 v4, v3, v2
	v_cndmask_b32_e32 v3, v3, v4, vcc
	v_add_u32_e32 v4, 1, v1
	v_cmp_ge_u32_e32 vcc, v3, v2
	v_add_u32_e32 v3, 1, v5
	s_nop 0
	v_cndmask_b32_e32 v1, v1, v4, vcc
	v_mul_lo_u32 v4, v2, v1
	v_add_u32_e32 v2, v4, v2
	v_cmp_ne_u32_e32 vcc, v3, v2
	s_and_saveexec_b64 s[8:9], vcc
	s_xor_b64 s[8:9], exec, s[8:9]
	s_cbranch_execz .LBB0_965
	s_waitcnt lgkmcnt(0)
	s_add_u32 s12, s78, 0x3500
	s_addc_u32 s13, s79, 0
	global_load_dword v0, v209, s[12:13] sc1
	s_waitcnt vmcnt(0)
	v_cmp_eq_u32_e32 vcc, v0, v1
	s_and_saveexec_b64 s[10:11], vcc
	s_cbranch_execz .LBB0_964
	s_mov_b32 s24, 1
	s_mov_b64 s[14:15], 0
	s_branch .LBB0_955
